# NSA: 32 exp-argument v_fma_f32 per step -> 16 v_pk_fma_f32 (scale/bias pair broadcast by op_sel), bit-identical
# baseline (speedup 1.0000x reference)
; #define LAS __attribute__((address_space(3)))
; #define MFMA32(a, b, c) __builtin_amdgcn_mfma_f32_32x32x16_bf16((a), (b), (c), 0, 0, 0)
; DI float fexp2(float x) { return __builtin_amdgcn_exp2f(x); }
; DI s16x4 vtr(const LAS unsigned char* p) { return __builtin_bit_cast(s16x4, __builtin_amdgcn_ds_read_tr16_b64_v4i16((LAS v4i16_t*)p)); }
; DI void flash_pv(FState& st, f32x16& p0, f32x16& p1, bool rowon, const LAS unsigned char* vb, int lane) {
;     ...
;     const float cl = rowon ? SM_C : 0.0f;
;     const float bl = rowon ? ((st.m == NINF) ? 0.0f : -st.m * SM_C) : NINF;
;     float sum = 0.f;
; #pragma unroll
;     for (int r = 0; r < 16; ++r) { p0[r] = fexp2(__builtin_fmaf(p0[r], cl, bl)); p1[r] = fexp2(__builtin_fmaf(p1[r], cl, bl)); sum += p0[r] + p1[r]; }
;     st.l += sum;
;     const int h = lane >> 5;
;     const int vx = (((lane & 15) >> 3) & 1) * 64;
;     const LAS unsigned char* vp = vb + (4 * h + ((lane & 15) >> 2)) * 128 + ((lane >> 4) & 1) * 32 + (lane & 3) * 8;
; #pragma unroll
;     for (int sub = 0; sub < 2; ++sub)
; #pragma unroll
;         for (int s2 = 0; s2 < 2; ++s2) {
;             const bf16x8 pf = pack8h(sub ? p1 : p0, s2);
;             const LAS unsigned char* vq = vp + (32 * sub + 16 * s2) * 128;
;             { const s16x4 lo = vtr(vq + vx), hi = vtr(vq + 1024 + vx); const bf16x8 vf = {lo[0], lo[1], lo[2], lo[3], hi[0], hi[1], hi[2], hi[3]}; st.o0 = MFMA32(vf, pf, st.o0); }
;             { const s16x4 lo = vtr(vq + (64 - vx)), hi = vtr(vq + 1024 + (64 - vx)); const bf16x8 vf = {lo[0], lo[1], lo[2], lo[3], hi[0], hi[1], hi[2], hi[3]}; st.o1 = MFMA32(vf, pf, st.o1); }
.LBB0_759:
	s_or_b64 exec, exec, s[4:5]
	v_pk_fma_f32 v[242:243], v[98:99], v[4:5], v[4:5] op_sel:[0,1,0] op_sel_hi:[1,1,0]
	v_exp_f32_e32 v12, v242
	v_pk_fma_f32 v[244:245], v[82:83], v[4:5], v[4:5] op_sel:[0,1,0] op_sel_hi:[1,1,0]
	v_exp_f32_e32 v246, v244
	s_waitcnt lgkmcnt(3)
	v_mfma_f32_32x32x16_bf16 v[130:145], v[226:229], v[154:157], v[130:145]
	v_exp_f32_e32 v6, v243
	v_exp_f32_e32 v2, v245
	v_add_f32_e32 v7, v12, v246
	s_add_i32 s77, s74, 1
	s_cmp_ge_u32 s77, s51
	v_pk_add_f32 v[8:9], v[6:7], v[2:3]
	v_pk_fma_f32 v[242:243], v[100:101], v[4:5], v[4:5] op_sel:[0,1,0] op_sel_hi:[1,1,0]
	v_pk_add_f32 v[98:99], v[8:9], v[8:9] op_sel_hi:[0,1]
	s_waitcnt lgkmcnt(2)
	v_mfma_f32_32x32x16_bf16 v[114:129], v[230:233], v[154:157], v[114:129]
	v_pk_fma_f32 v[244:245], v[84:85], v[4:5], v[4:5] op_sel:[0,1,0] op_sel_hi:[1,1,0]
	v_exp_f32_e32 v7, v242
	v_exp_f32_e32 v247, v244
	v_exp_f32_e32 v8, v243
	v_exp_f32_e32 v98, v245
	v_add_f32_e32 v9, v7, v247
	v_cvt_pk_bf16_f32 v6, v12, v6
	v_cvt_pk_bf16_f32 v7, v7, v8
	s_waitcnt lgkmcnt(1)
	v_mfma_f32_32x32x16_bf16 v[130:145], v[234:237], v[158:161], v[130:145]
	v_pk_add_f32 v[10:11], v[8:9], v[98:99]
	v_pk_fma_f32 v[242:243], v[102:103], v[4:5], v[4:5] op_sel:[0,1,0] op_sel_hi:[1,1,0]
	v_pk_add_f32 v[100:101], v[10:11], v[10:11] op_sel_hi:[0,1]
	v_pk_fma_f32 v[244:245], v[86:87], v[4:5], v[4:5] op_sel:[0,1,0] op_sel_hi:[1,1,0]
	v_exp_f32_e32 v99, v244
	v_exp_f32_e32 v9, v242
	v_exp_f32_e32 v14, v243
	v_exp_f32_e32 v100, v245
	s_waitcnt lgkmcnt(0)
	v_mfma_f32_32x32x16_bf16 v[114:129], v[238:241], v[158:161], v[114:129]
	v_add_f32_e32 v15, v9, v99
	v_cvt_pk_bf16_f32 v8, v9, v14
	v_pk_add_f32 v[10:11], v[14:15], v[100:101]
	s_nop 0
	v_pk_add_f32 v[86:87], v[10:11], v[10:11] op_sel_hi:[0,1]
	v_pk_fma_f32 v[242:243], v[104:105], v[4:5], v[4:5] op_sel:[0,1,0] op_sel_hi:[1,1,0]
	v_exp_f32_e32 v15, v242
	v_pk_fma_f32 v[244:245], v[88:89], v[4:5], v[4:5] op_sel:[0,1,0] op_sel_hi:[1,1,0]
	v_exp_f32_e32 v101, v244
	v_exp_f32_e32 v16, v243
	v_exp_f32_e32 v86, v245
	v_add_f32_e32 v17, v15, v101
	v_cvt_pk_bf16_f32 v9, v15, v16
	v_pk_add_f32 v[10:11], v[16:17], v[86:87]
	s_nop 0
	v_pk_add_f32 v[88:89], v[10:11], v[10:11] op_sel_hi:[0,1]
	v_pk_fma_f32 v[242:243], v[106:107], v[4:5], v[4:5] op_sel:[0,1,0] op_sel_hi:[1,1,0]
	v_exp_f32_e32 v87, v242
	v_pk_fma_f32 v[244:245], v[90:91], v[4:5], v[4:5] op_sel:[0,1,0] op_sel_hi:[1,1,0]
	v_exp_f32_e32 v248, v244
	v_exp_f32_e32 v90, v243
	v_exp_f32_e32 v88, v245
	v_pk_fma_f32 v[242:243], v[108:109], v[4:5], v[4:5] op_sel:[0,1,0] op_sel_hi:[1,1,0]
	v_exp_f32_e32 v107, v242
	v_pk_fma_f32 v[244:245], v[92:93], v[4:5], v[4:5] op_sel:[0,1,0] op_sel_hi:[1,1,0]
	v_add_f32_e32 v91, v87, v248
	v_exp_f32_e32 v108, v244
	v_pk_add_f32 v[10:11], v[90:91], v[88:89]
	v_pk_fma_f32 v[250:251], v[112:113], v[4:5], v[4:5] op_sel:[0,1,0] op_sel_hi:[1,1,0]
	v_pk_add_f32 v[102:103], v[10:11], v[10:11] op_sel_hi:[0,1]
	v_exp_f32_e32 v104, v243
	v_exp_f32_e32 v102, v245
	ds_read_b64_tr_b16 v[10:11], v218 offset:8192
	ds_read_b64_tr_b16 v[12:13], v218 offset:9216
	ds_read_b64_tr_b16 v[14:15], v217 offset:8256
	ds_read_b64_tr_b16 v[16:17], v217 offset:9280
	ds_read_b64_tr_b16 v[82:83], v218 offset:10240
	ds_read_b64_tr_b16 v[84:85], v218 offset:11264
	s_waitcnt lgkmcnt(4)
	v_mfma_f32_32x32x16_bf16 v[66:81], v[10:13], v[6:9], v[66:81]
	v_pk_fma_f32 v[242:243], v[110:111], v[4:5], v[4:5] op_sel:[0,1,0] op_sel_hi:[1,1,0]
	v_exp_f32_e32 v89, v242
	v_exp_f32_e32 v92, v243
	v_exp_f32_e32 v109, v250
	v_add_f32_e32 v105, v107, v108
	ds_read_b64_tr_b16 v[10:11], v217 offset:10304
	ds_read_b64_tr_b16 v[12:13], v217 offset:11328
	s_waitcnt lgkmcnt(4)
	v_mfma_f32_32x32x16_bf16 v[50:65], v[14:17], v[6:9], v[50:65]
	v_exp_f32_e32 v106, v251
	v_cvt_pk_bf16_f32 v6, v87, v90
	v_cvt_pk_bf16_f32 v7, v107, v104
	v_cvt_pk_bf16_f32 v8, v89, v92
	v_cvt_pk_bf16_f32 v9, v109, v106
	v_pk_add_f32 v[14:15], v[104:105], v[102:103]
	s_waitcnt lgkmcnt(2)
	v_mfma_f32_32x32x16_bf16 v[66:81], v[82:85], v[6:9], v[66:81]
	v_add_f32_e64 v90, v14, v14
	v_add_f32_e64 v91, v14, v15
	v_pk_fma_f32 v[242:243], v[94:95], v[4:5], v[4:5] op_sel:[0,1,0] op_sel_hi:[1,1,0]
	v_exp_f32_e32 v94, v242
	ds_read_b64_tr_b16 v[14:15], v218 offset:12288
	ds_read_b64_tr_b16 v[16:17], v218 offset:13312
	v_exp_f32_e32 v90, v243
	v_add_f32_e32 v93, v89, v94
	s_waitcnt lgkmcnt(2)
	v_mfma_f32_32x32x16_bf16 v[50:65], v[10:13], v[6:9], v[50:65]
	v_cvt_pk_bf16_f32 v6, v246, v2
	v_cvt_pk_bf16_f32 v7, v247, v98
	v_cvt_pk_bf16_f32 v8, v99, v100
	v_cvt_pk_bf16_f32 v9, v101, v86
	ds_read_b64_tr_b16 v[10:11], v218 offset:14336
	ds_read_b64_tr_b16 v[12:13], v218 offset:15360
	v_pk_add_f32 v[82:83], v[92:93], v[90:91]
	v_pk_fma_f32 v[242:243], v[96:97], v[4:5], v[4:5] op_sel:[0,1,0] op_sel_hi:[1,1,0]
	s_waitcnt lgkmcnt(2)
	v_mfma_f32_32x32x16_bf16 v[66:81], v[14:17], v[6:9], v[66:81]
	ds_read_b64_tr_b16 v[14:15], v217 offset:12352
	ds_read_b64_tr_b16 v[16:17], v217 offset:13376
	v_add_f32_e64 v86, v82, v82
	v_add_f32_e64 v87, v82, v83
	ds_read_b64_tr_b16 v[82:83], v217 offset:14400
	ds_read_b64_tr_b16 v[84:85], v217 offset:15424
	v_exp_f32_e32 v2, v242
	v_exp_f32_e32 v86, v243
	v_cvt_pk_bf16_f32 v4, v248, v88
	s_waitcnt lgkmcnt(2)
	v_mfma_f32_32x32x16_bf16 v[50:65], v[14:17], v[6:9], v[50:65]
	v_cvt_pk_bf16_f32 v5, v108, v102
	v_cvt_pk_bf16_f32 v6, v94, v90
	v_cvt_pk_bf16_f32 v7, v2, v86
	v_add_f32_e32 v107, v109, v2
	v_add_f32_e64 v8, v106, v86
	v_add_f32_e64 v9, v107, v87
	v_add_f32_e32 v2, v8, v9
	v_mfma_f32_32x32x16_bf16 v[66:81], v[10:13], v[4:7], v[66:81]
	v_add_f32_e32 v214, v214, v2
	s_waitcnt lgkmcnt(0)
	v_mfma_f32_32x32x16_bf16 v[50:65], v[82:85], v[4:7], v[50:65]
	s_cbranch_scc1 .LBB0_780
	s_movk_i32 s76, 0x4000
	s_add_i32 s4, s74, 5
	s_cmp_ge_u32 s4, s51
	s_waitcnt vmcnt(1)
	ds_write_b128 v205, v[182:185] offset:32768
	s_waitcnt vmcnt(0)
	ds_write_b128 v212, v[178:181] offset:40960
	s_waitcnt lgkmcnt(0)
	s_barrier
	s_cbranch_scc1 .LBB0_762
	s_cmp_gt_u32 s4, s69
	s_cselect_b64 s[8:9], -1, 0
	s_mov_b32 s5, s52
	s_and_b64 s[8:9], s[8:9], exec
	s_cselect_b32 s4, s5, s4
	s_cselect_b32 s16, 0x1000, s65
	s_cselect_b32 s8, s64, 0x500
	s_lshl_b32 s4, s4, 6
	s_mov_b32 s9, s17
	v_mad_i64_i32 v[4:5], s[4:5], s4, v199, v[192:193]
	v_lshl_add_u64 v[6:7], v[4:5], 0, s[8:9]
	v_lshl_add_u64 v[4:5], v[4:5], 0, s[16:17]
	global_load_dwordx4 v[182:185], v[6:7], off
	global_load_dwordx4 v[178:181], v[4:5], off

; #define LAS __attribute__((address_space(3)))
; #define MFMA32(a, b, c) __builtin_amdgcn_mfma_f32_32x32x16_bf16((a), (b), (c), 0, 0, 0)
; DI float fexp2(float x) { return __builtin_amdgcn_exp2f(x); }
; DI s16x4 vtr(const LAS unsigned char* p) { return __builtin_bit_cast(s16x4, __builtin_amdgcn_ds_read_tr16_b64_v4i16((LAS v4i16_t*)p)); }
; DI void flash_qk(const LAS unsigned char* kb, const bf16x8 (&qf)[4], f32x16& p0, f32x16& p1, int r32, int h) {
;     ...
;     for (int s = 0; s < 4; ++s) {
;         const int off = r32 * 128 + (((2 * s + h) ^ sw) << 4);
;         const bf16x8 a0 = *(const LAS bf16x8*)(kb + off), a1 = *(const LAS bf16x8*)(kb + off + 4096);
;         p0 = MFMA32(a0, qf[s], p0); p1 = MFMA32(a1, qf[s], p1);
;     }
; DI void flash_pv(FState& st, f32x16& p0, f32x16& p1, bool rowon, const LAS unsigned char* vb, int lane) {
;     ...
;     const float cl = rowon ? SM_C : 0.0f;
;     const float bl = rowon ? ((st.m == NINF) ? 0.0f : -st.m * SM_C) : NINF;
;     float sum = 0.f;
; #pragma unroll
;     for (int r = 0; r < 16; ++r) { p0[r] = fexp2(__builtin_fmaf(p0[r], cl, bl)); p1[r] = fexp2(__builtin_fmaf(p1[r], cl, bl)); sum += p0[r] + p1[r]; }
;     st.l += sum;
;     const int h = lane >> 5;
;     const int vx = (((lane & 15) >> 3) & 1) * 64;
;     const LAS unsigned char* vp = vb + (4 * h + ((lane & 15) >> 2)) * 128 + ((lane >> 4) & 1) * 32 + (lane & 3) * 8;
; #pragma unroll
;     for (int sub = 0; sub < 2; ++sub)
; #pragma unroll
;         for (int s2 = 0; s2 < 2; ++s2) {
;             const bf16x8 pf = pack8h(sub ? p1 : p0, s2);
;             const LAS unsigned char* vq = vp + (32 * sub + 16 * s2) * 128;
;             { const s16x4 lo = vtr(vq + vx), hi = vtr(vq + 1024 + vx); const bf16x8 vf = {lo[0], lo[1], lo[2], lo[3], hi[0], hi[1], hi[2], hi[3]}; st.o0 = MFMA32(vf, pf, st.o0); }
;             { const s16x4 lo = vtr(vq + (64 - vx)), hi = vtr(vq + 1024 + (64 - vx)); const bf16x8 vf = {lo[0], lo[1], lo[2], lo[3], hi[0], hi[1], hi[2], hi[3]}; st.o1 = MFMA32(vf, pf, st.o1); }
;         }
.LBB0_778:
	s_or_b64 exec, exec, s[4:5]
	v_pk_fma_f32 v[242:243], v[130:131], v[4:5], v[4:5] op_sel:[0,1,0] op_sel_hi:[1,1,0]
	v_exp_f32_e32 v12, v242
	v_pk_fma_f32 v[244:245], v[114:115], v[4:5], v[4:5] op_sel:[0,1,0] op_sel_hi:[1,1,0]
	v_exp_f32_e32 v246, v244
	s_waitcnt lgkmcnt(3)
	v_mfma_f32_32x32x16_bf16 v[98:113], v[226:229], v[154:157], v[98:113]
	v_exp_f32_e32 v6, v243
	v_exp_f32_e32 v2, v245
	v_add_f32_e32 v7, v12, v246
	v_pk_add_f32 v[8:9], v[6:7], v[2:3]
	s_nop 0
	v_pk_add_f32 v[130:131], v[8:9], v[8:9] op_sel_hi:[0,1]
	v_pk_fma_f32 v[242:243], v[132:133], v[4:5], v[4:5] op_sel:[0,1,0] op_sel_hi:[1,1,0]
	v_pk_fma_f32 v[244:245], v[116:117], v[4:5], v[4:5] op_sel:[0,1,0] op_sel_hi:[1,1,0]
	s_waitcnt lgkmcnt(2)
	v_mfma_f32_32x32x16_bf16 v[82:97], v[230:233], v[154:157], v[82:97]
	v_exp_f32_e32 v7, v242
	v_exp_f32_e32 v247, v244
	v_exp_f32_e32 v8, v243
	v_exp_f32_e32 v130, v245
	v_add_f32_e32 v9, v7, v247
	v_cvt_pk_bf16_f32 v6, v12, v6
	v_cvt_pk_bf16_f32 v7, v7, v8
	v_pk_add_f32 v[10:11], v[8:9], v[130:131]
	s_waitcnt lgkmcnt(1)
	v_mfma_f32_32x32x16_bf16 v[98:113], v[234:237], v[158:161], v[98:113]
	v_pk_fma_f32 v[242:243], v[134:135], v[4:5], v[4:5] op_sel:[0,1,0] op_sel_hi:[1,1,0]
	v_pk_add_f32 v[132:133], v[10:11], v[10:11] op_sel_hi:[0,1]
	v_pk_fma_f32 v[244:245], v[118:119], v[4:5], v[4:5] op_sel:[0,1,0] op_sel_hi:[1,1,0]
	v_exp_f32_e32 v131, v244
	v_exp_f32_e32 v9, v242
	v_exp_f32_e32 v14, v243
	v_exp_f32_e32 v132, v245
	v_add_f32_e32 v15, v9, v131
	s_waitcnt lgkmcnt(0)
	v_mfma_f32_32x32x16_bf16 v[82:97], v[238:241], v[158:161], v[82:97]
	v_cvt_pk_bf16_f32 v8, v9, v14
	v_pk_add_f32 v[10:11], v[14:15], v[132:133]
	s_nop 0
	v_pk_add_f32 v[118:119], v[10:11], v[10:11] op_sel_hi:[0,1]
	v_pk_fma_f32 v[242:243], v[136:137], v[4:5], v[4:5] op_sel:[0,1,0] op_sel_hi:[1,1,0]
	v_exp_f32_e32 v15, v242
	v_pk_fma_f32 v[244:245], v[120:121], v[4:5], v[4:5] op_sel:[0,1,0] op_sel_hi:[1,1,0]
	v_exp_f32_e32 v133, v244
	v_exp_f32_e32 v16, v243
	v_exp_f32_e32 v118, v245
	v_add_f32_e32 v17, v15, v133
	v_cvt_pk_bf16_f32 v9, v15, v16
	v_pk_add_f32 v[10:11], v[16:17], v[118:119]
	s_nop 0
	v_pk_add_f32 v[120:121], v[10:11], v[10:11] op_sel_hi:[0,1]
	v_pk_fma_f32 v[242:243], v[138:139], v[4:5], v[4:5] op_sel:[0,1,0] op_sel_hi:[1,1,0]
	v_exp_f32_e32 v119, v242
	v_pk_fma_f32 v[244:245], v[122:123], v[4:5], v[4:5] op_sel:[0,1,0] op_sel_hi:[1,1,0]
	v_exp_f32_e32 v248, v244
	v_exp_f32_e32 v122, v243
	v_exp_f32_e32 v120, v245
	v_pk_fma_f32 v[242:243], v[140:141], v[4:5], v[4:5] op_sel:[0,1,0] op_sel_hi:[1,1,0]
	v_exp_f32_e32 v139, v242
	v_pk_fma_f32 v[244:245], v[124:125], v[4:5], v[4:5] op_sel:[0,1,0] op_sel_hi:[1,1,0]
	v_add_f32_e32 v123, v119, v248
	v_exp_f32_e32 v140, v244
	v_pk_add_f32 v[10:11], v[122:123], v[120:121]
	v_pk_fma_f32 v[250:251], v[144:145], v[4:5], v[4:5] op_sel:[0,1,0] op_sel_hi:[1,1,0]
	v_pk_add_f32 v[134:135], v[10:11], v[10:11] op_sel_hi:[0,1]
	v_exp_f32_e32 v136, v243
	v_exp_f32_e32 v134, v245
	ds_read_b64_tr_b16 v[10:11], v218 offset:24576
	ds_read_b64_tr_b16 v[12:13], v218 offset:25600
	ds_read_b64_tr_b16 v[14:15], v217 offset:24640
	ds_read_b64_tr_b16 v[16:17], v217 offset:25664
	ds_read_b64_tr_b16 v[114:115], v218 offset:26624
	ds_read_b64_tr_b16 v[116:117], v218 offset:27648
	s_waitcnt lgkmcnt(4)
	v_mfma_f32_32x32x16_bf16 v[66:81], v[10:13], v[6:9], v[66:81]
	v_pk_fma_f32 v[242:243], v[142:143], v[4:5], v[4:5] op_sel:[0,1,0] op_sel_hi:[1,1,0]
	v_exp_f32_e32 v125, v242
	v_exp_f32_e32 v124, v243
	v_exp_f32_e32 v142, v250
	v_add_f32_e32 v137, v139, v140
	ds_read_b64_tr_b16 v[10:11], v217 offset:26688
	ds_read_b64_tr_b16 v[12:13], v217 offset:27712
	s_waitcnt lgkmcnt(4)
	v_mfma_f32_32x32x16_bf16 v[50:65], v[14:17], v[6:9], v[50:65]
	v_exp_f32_e32 v138, v251
	v_cvt_pk_bf16_f32 v6, v119, v122
	v_cvt_pk_bf16_f32 v7, v139, v136
	v_cvt_pk_bf16_f32 v8, v125, v124
	v_cvt_pk_bf16_f32 v9, v142, v138
	v_pk_add_f32 v[14:15], v[136:137], v[134:135]
	s_waitcnt lgkmcnt(2)
	v_mfma_f32_32x32x16_bf16 v[66:81], v[114:117], v[6:9], v[66:81]
	v_add_f32_e64 v122, v14, v14
	v_add_f32_e64 v123, v14, v15
	v_pk_fma_f32 v[242:243], v[126:127], v[4:5], v[4:5] op_sel:[0,1,0] op_sel_hi:[1,1,0]
	v_exp_f32_e32 v126, v242
	ds_read_b64_tr_b16 v[14:15], v218 offset:28672
	ds_read_b64_tr_b16 v[16:17], v218 offset:29696
	v_exp_f32_e32 v122, v243
	v_add_f32_e32 v125, v125, v126
	s_waitcnt lgkmcnt(2)
	v_mfma_f32_32x32x16_bf16 v[50:65], v[10:13], v[6:9], v[50:65]
	v_cvt_pk_bf16_f32 v6, v246, v2
	v_cvt_pk_bf16_f32 v7, v247, v130
	v_cvt_pk_bf16_f32 v8, v131, v132
	v_cvt_pk_bf16_f32 v9, v133, v118
	ds_read_b64_tr_b16 v[10:11], v218 offset:30720
	ds_read_b64_tr_b16 v[12:13], v218 offset:31744
	v_pk_add_f32 v[114:115], v[124:125], v[122:123]
	v_pk_fma_f32 v[242:243], v[128:129], v[4:5], v[4:5] op_sel:[0,1,0] op_sel_hi:[1,1,0]
	s_waitcnt lgkmcnt(2)
	v_mfma_f32_32x32x16_bf16 v[66:81], v[14:17], v[6:9], v[66:81]
	ds_read_b64_tr_b16 v[14:15], v217 offset:28736
	ds_read_b64_tr_b16 v[16:17], v217 offset:29760
	v_add_f32_e64 v118, v114, v114
	v_add_f32_e64 v119, v114, v115
	ds_read_b64_tr_b16 v[114:115], v217 offset:30784
	ds_read_b64_tr_b16 v[116:117], v217 offset:31808
	v_exp_f32_e32 v2, v242
	v_exp_f32_e32 v118, v243
	v_cvt_pk_bf16_f32 v4, v248, v120
	s_waitcnt lgkmcnt(2)
	v_mfma_f32_32x32x16_bf16 v[50:65], v[14:17], v[6:9], v[50:65]
	v_cvt_pk_bf16_f32 v5, v140, v134
	v_cvt_pk_bf16_f32 v6, v126, v122
	v_cvt_pk_bf16_f32 v7, v2, v118
	v_add_f32_e32 v139, v142, v2
	v_add_f32_e64 v8, v138, v118
	v_add_f32_e64 v9, v139, v119
	v_add_f32_e32 v2, v8, v9
	v_mfma_f32_32x32x16_bf16 v[66:81], v[10:13], v[4:7], v[66:81]
	v_add_f32_e32 v214, v214, v2
	s_waitcnt lgkmcnt(0)
	v_mfma_f32_32x32x16_bf16 v[50:65], v[114:117], v[4:7], v[50:65]
	s_add_i32 s76, s74, 2
	s_cmp_ge_u32 s76, s51
	s_cbranch_scc0 .LBB0_781

; #define LAS __attribute__((address_space(3)))
; #define MFMA32(a, b, c) __builtin_amdgcn_mfma_f32_32x32x16_bf16((a), (b), (c), 0, 0, 0)
; DI float fexp2(float x) { return __builtin_amdgcn_exp2f(x); }
; DI s16x4 vtr(const LAS unsigned char* p) { return __builtin_bit_cast(s16x4, __builtin_amdgcn_ds_read_tr16_b64_v4i16((LAS v4i16_t*)p)); }
; DI void flash_qk(const LAS unsigned char* kb, const bf16x8 (&qf)[4], f32x16& p0, f32x16& p1, int r32, int h) {
;     ...
;     for (int s = 0; s < 4; ++s) {
;         const int off = r32 * 128 + (((2 * s + h) ^ sw) << 4);
;         const bf16x8 a0 = *(const LAS bf16x8*)(kb + off), a1 = *(const LAS bf16x8*)(kb + off + 4096);
;         p0 = MFMA32(a0, qf[s], p0); p1 = MFMA32(a1, qf[s], p1);
;     }
; DI void flash_pv(FState& st, f32x16& p0, f32x16& p1, bool rowon, const LAS unsigned char* vb, int lane) {
;     ...
;     const float cl = rowon ? SM_C : 0.0f;
;     const float bl = rowon ? ((st.m == NINF) ? 0.0f : -st.m * SM_C) : NINF;
;     float sum = 0.f;
; #pragma unroll
;     for (int r = 0; r < 16; ++r) { p0[r] = fexp2(__builtin_fmaf(p0[r], cl, bl)); p1[r] = fexp2(__builtin_fmaf(p1[r], cl, bl)); sum += p0[r] + p1[r]; }
;     st.l += sum;
;     const int h = lane >> 5;
;     const int vx = (((lane & 15) >> 3) & 1) * 64;
;     const LAS unsigned char* vp = vb + (4 * h + ((lane & 15) >> 2)) * 128 + ((lane >> 4) & 1) * 32 + (lane & 3) * 8;
; #pragma unroll
;     for (int sub = 0; sub < 2; ++sub)
; #pragma unroll
;         for (int s2 = 0; s2 < 2; ++s2) {
;             const bf16x8 pf = pack8h(sub ? p1 : p0, s2);
;             const LAS unsigned char* vq = vp + (32 * sub + 16 * s2) * 128;
;             { const s16x4 lo = vtr(vq + vx), hi = vtr(vq + 1024 + vx); const bf16x8 vf = {lo[0], lo[1], lo[2], lo[3], hi[0], hi[1], hi[2], hi[3]}; st.o0 = MFMA32(vf, pf, st.o0); }
;             { const s16x4 lo = vtr(vq + (64 - vx)), hi = vtr(vq + 1024 + (64 - vx)); const bf16x8 vf = {lo[0], lo[1], lo[2], lo[3], hi[0], hi[1], hi[2], hi[3]}; st.o1 = MFMA32(vf, pf, st.o1); }
;         }
.LBB0_799:
	s_or_b64 exec, exec, s[4:5]
	v_pk_fma_f32 v[242:243], v[98:99], v[4:5], v[4:5] op_sel:[0,1,0] op_sel_hi:[1,1,0]
	v_exp_f32_e32 v246, v242
	v_pk_fma_f32 v[244:245], v[82:83], v[4:5], v[4:5] op_sel:[0,1,0] op_sel_hi:[1,1,0]
	v_exp_f32_e32 v247, v244
	s_waitcnt lgkmcnt(3)
	v_mfma_f32_32x32x16_bf16 v[130:145], v[226:229], v[154:157], v[130:145]
	v_exp_f32_e32 v10, v243
	v_exp_f32_e32 v2, v245
	v_add_f32_e32 v11, v246, v247
	v_pk_add_f32 v[6:7], v[10:11], v[2:3]
	s_nop 0
	v_pk_add_f32 v[98:99], v[6:7], v[6:7] op_sel_hi:[0,1]
	v_pk_fma_f32 v[242:243], v[100:101], v[4:5], v[4:5] op_sel:[0,1,0] op_sel_hi:[1,1,0]
	v_exp_f32_e32 v11, v242
	s_waitcnt lgkmcnt(2)
	v_mfma_f32_32x32x16_bf16 v[114:129], v[230:233], v[154:157], v[114:129]
	v_pk_fma_f32 v[244:245], v[84:85], v[4:5], v[4:5] op_sel:[0,1,0] op_sel_hi:[1,1,0]
	v_exp_f32_e32 v248, v244
	v_exp_f32_e32 v12, v243
	v_exp_f32_e32 v98, v245
	v_add_f32_e32 v13, v11, v248
	v_cvt_pk_bf16_f32 v10, v246, v10
	v_cvt_pk_bf16_f32 v11, v11, v12
	v_pk_add_f32 v[6:7], v[12:13], v[98:99]
	s_waitcnt lgkmcnt(1)
	v_mfma_f32_32x32x16_bf16 v[130:145], v[234:237], v[158:161], v[130:145]
	s_nop 0
	v_pk_add_f32 v[100:101], v[6:7], v[6:7] op_sel_hi:[0,1]
	v_pk_fma_f32 v[242:243], v[102:103], v[4:5], v[4:5] op_sel:[0,1,0] op_sel_hi:[1,1,0]
	v_exp_f32_e32 v13, v242
	v_pk_fma_f32 v[244:245], v[86:87], v[4:5], v[4:5] op_sel:[0,1,0] op_sel_hi:[1,1,0]
	v_exp_f32_e32 v99, v244
	v_exp_f32_e32 v14, v243
	v_exp_f32_e32 v100, v245
	s_waitcnt lgkmcnt(0)
	v_mfma_f32_32x32x16_bf16 v[114:129], v[238:241], v[158:161], v[114:129]
	v_add_f32_e32 v15, v13, v99
	v_cvt_pk_bf16_f32 v12, v13, v14
	v_pk_add_f32 v[6:7], v[14:15], v[100:101]
	s_nop 0
	v_pk_add_f32 v[86:87], v[6:7], v[6:7] op_sel_hi:[0,1]
	v_pk_fma_f32 v[242:243], v[104:105], v[4:5], v[4:5] op_sel:[0,1,0] op_sel_hi:[1,1,0]
	v_exp_f32_e32 v15, v242
	v_pk_fma_f32 v[244:245], v[88:89], v[4:5], v[4:5] op_sel:[0,1,0] op_sel_hi:[1,1,0]
	v_exp_f32_e32 v101, v244
	v_exp_f32_e32 v16, v243
	v_exp_f32_e32 v86, v245
	v_add_f32_e32 v17, v15, v101
	v_cvt_pk_bf16_f32 v13, v15, v16
	v_pk_add_f32 v[6:7], v[16:17], v[86:87]
	s_nop 0
	v_pk_add_f32 v[88:89], v[6:7], v[6:7] op_sel_hi:[0,1]
	v_pk_fma_f32 v[242:243], v[106:107], v[4:5], v[4:5] op_sel:[0,1,0] op_sel_hi:[1,1,0]
	v_exp_f32_e32 v87, v242
	v_pk_fma_f32 v[244:245], v[90:91], v[4:5], v[4:5] op_sel:[0,1,0] op_sel_hi:[1,1,0]
	v_exp_f32_e32 v249, v244
	v_exp_f32_e32 v90, v243
	v_exp_f32_e32 v88, v245
	v_pk_fma_f32 v[242:243], v[108:109], v[4:5], v[4:5] op_sel:[0,1,0] op_sel_hi:[1,1,0]
	v_exp_f32_e32 v107, v242
	v_pk_fma_f32 v[244:245], v[92:93], v[4:5], v[4:5] op_sel:[0,1,0] op_sel_hi:[1,1,0]
	v_add_f32_e32 v91, v87, v249
	v_exp_f32_e32 v108, v244
	v_pk_add_f32 v[6:7], v[90:91], v[88:89]
	v_pk_fma_f32 v[250:251], v[112:113], v[4:5], v[4:5] op_sel:[0,1,0] op_sel_hi:[1,1,0]
	v_pk_add_f32 v[102:103], v[6:7], v[6:7] op_sel_hi:[0,1]
	v_exp_f32_e32 v104, v243
	v_exp_f32_e32 v102, v245
	ds_read_b64_tr_b16 v[6:7], v218 offset:40960
	ds_read_b64_tr_b16 v[8:9], v218 offset:41984
	ds_read_b64_tr_b16 v[14:15], v217 offset:41024
	ds_read_b64_tr_b16 v[16:17], v217 offset:42048
	ds_read_b64_tr_b16 v[82:83], v218 offset:43008
	ds_read_b64_tr_b16 v[84:85], v218 offset:44032
	s_waitcnt lgkmcnt(4)
	v_mfma_f32_32x32x16_bf16 v[66:81], v[6:9], v[10:13], v[66:81]
	v_pk_fma_f32 v[242:243], v[110:111], v[4:5], v[4:5] op_sel:[0,1,0] op_sel_hi:[1,1,0]
	v_exp_f32_e32 v89, v242
	v_exp_f32_e32 v92, v243
	v_exp_f32_e32 v109, v250
	v_add_f32_e32 v105, v107, v108
	ds_read_b64_tr_b16 v[6:7], v217 offset:43072
	ds_read_b64_tr_b16 v[8:9], v217 offset:44096
	s_waitcnt lgkmcnt(4)
	v_mfma_f32_32x32x16_bf16 v[50:65], v[14:17], v[10:13], v[50:65]
	v_exp_f32_e32 v106, v251
	v_cvt_pk_bf16_f32 v10, v87, v90
	v_cvt_pk_bf16_f32 v11, v107, v104
	v_cvt_pk_bf16_f32 v12, v89, v92
	v_cvt_pk_bf16_f32 v13, v109, v106
	v_pk_add_f32 v[14:15], v[104:105], v[102:103]
	s_waitcnt lgkmcnt(2)
	v_mfma_f32_32x32x16_bf16 v[66:81], v[82:85], v[10:13], v[66:81]
	v_add_f32_e64 v90, v14, v14
	v_add_f32_e64 v91, v14, v15
	v_pk_fma_f32 v[242:243], v[94:95], v[4:5], v[4:5] op_sel:[0,1,0] op_sel_hi:[1,1,0]
	v_exp_f32_e32 v94, v242
	ds_read_b64_tr_b16 v[14:15], v218 offset:45056
	ds_read_b64_tr_b16 v[16:17], v218 offset:46080
	v_exp_f32_e32 v90, v243
	v_add_f32_e32 v93, v89, v94
	s_waitcnt lgkmcnt(2)
	v_mfma_f32_32x32x16_bf16 v[50:65], v[6:9], v[10:13], v[50:65]
	v_cvt_pk_bf16_f32 v6, v247, v2
	v_cvt_pk_bf16_f32 v7, v248, v98
	v_cvt_pk_bf16_f32 v8, v99, v100
	v_cvt_pk_bf16_f32 v9, v101, v86
	ds_read_b64_tr_b16 v[10:11], v218 offset:47104
	ds_read_b64_tr_b16 v[12:13], v218 offset:48128
	v_pk_add_f32 v[82:83], v[92:93], v[90:91]
	v_pk_fma_f32 v[242:243], v[96:97], v[4:5], v[4:5] op_sel:[0,1,0] op_sel_hi:[1,1,0]
	s_waitcnt lgkmcnt(2)
	v_mfma_f32_32x32x16_bf16 v[66:81], v[14:17], v[6:9], v[66:81]
	ds_read_b64_tr_b16 v[14:15], v217 offset:45120
	ds_read_b64_tr_b16 v[16:17], v217 offset:46144
	v_add_f32_e64 v86, v82, v82
	v_add_f32_e64 v87, v82, v83
	ds_read_b64_tr_b16 v[82:83], v217 offset:47168
	ds_read_b64_tr_b16 v[84:85], v217 offset:48192
	v_exp_f32_e32 v2, v242
	v_exp_f32_e32 v86, v243
	v_cvt_pk_bf16_f32 v4, v249, v88
	s_waitcnt lgkmcnt(2)
	v_mfma_f32_32x32x16_bf16 v[50:65], v[14:17], v[6:9], v[50:65]
	v_cvt_pk_bf16_f32 v5, v108, v102
	v_cvt_pk_bf16_f32 v6, v94, v90
	v_cvt_pk_bf16_f32 v7, v2, v86
	v_add_f32_e32 v107, v109, v2
	v_add_f32_e64 v8, v106, v86
	v_add_f32_e64 v9, v107, v87
	v_add_f32_e32 v2, v8, v9
	v_mfma_f32_32x32x16_bf16 v[66:81], v[10:13], v[4:7], v[66:81]
	v_add_f32_e32 v214, v214, v2
	s_waitcnt lgkmcnt(0)
	v_mfma_f32_32x32x16_bf16 v[50:65], v[82:85], v[4:7], v[50:65]
	s_add_i32 s52, s52, -3
	s_andn2_b64 vcc, exec, s[6:7]
	s_add_i32 s53, s53, 0xc000
	s_cbranch_vccz .LBB0_712

; #define LAS __attribute__((address_space(3)))
; #define MFMA32(a, b, c) __builtin_amdgcn_mfma_f32_32x32x16_bf16((a), (b), (c), 0, 0, 0)
; DI float fexp2(float x) { return __builtin_amdgcn_exp2f(x); }
; DI s16x4 vtr(const LAS unsigned char* p) { return __builtin_bit_cast(s16x4, __builtin_amdgcn_ds_read_tr16_b64_v4i16((LAS v4i16_t*)p)); }
; DI void flash_pv(FState& st, f32x16& p0, f32x16& p1, bool rowon, const LAS unsigned char* vb, int lane) {
;     ...
;     const float cl = rowon ? SM_C : 0.0f;
;     const float bl = rowon ? ((st.m == NINF) ? 0.0f : -st.m * SM_C) : NINF;
;     float sum = 0.f;
; #pragma unroll
;     for (int r = 0; r < 16; ++r) { p0[r] = fexp2(__builtin_fmaf(p0[r], cl, bl)); p1[r] = fexp2(__builtin_fmaf(p1[r], cl, bl)); sum += p0[r] + p1[r]; }
;     st.l += sum;
;     const int h = lane >> 5;
;     const int vx = (((lane & 15) >> 3) & 1) * 64;
;     const LAS unsigned char* vp = vb + (4 * h + ((lane & 15) >> 2)) * 128 + ((lane >> 4) & 1) * 32 + (lane & 3) * 8;
; #pragma unroll
;     for (int sub = 0; sub < 2; ++sub)
; #pragma unroll
;         for (int s2 = 0; s2 < 2; ++s2) {
;             const bf16x8 pf = pack8h(sub ? p1 : p0, s2);
;             const LAS unsigned char* vq = vp + (32 * sub + 16 * s2) * 128;
;             { const s16x4 lo = vtr(vq + vx), hi = vtr(vq + 1024 + vx); const bf16x8 vf = {lo[0], lo[1], lo[2], lo[3], hi[0], hi[1], hi[2], hi[3]}; st.o0 = MFMA32(vf, pf, st.o0); }
;             { const s16x4 lo = vtr(vq + (64 - vx)), hi = vtr(vq + 1024 + (64 - vx)); const bf16x8 vf = {lo[0], lo[1], lo[2], lo[3], hi[0], hi[1], hi[2], hi[3]}; st.o1 = MFMA32(vf, pf, st.o1); }
;         }
.Lnq_759:
	s_or_b64 exec, exec, s[4:5]
	v_pk_fma_f32 v[242:243], v[130:131], v[4:5], v[4:5] op_sel:[0,1,0] op_sel_hi:[1,1,0]
	v_exp_f32_e32 v12, v242
	v_pk_fma_f32 v[244:245], v[114:115], v[4:5], v[4:5] op_sel:[0,1,0] op_sel_hi:[1,1,0]
	v_exp_f32_e32 v246, v244
	s_waitcnt lgkmcnt(3)
	v_mfma_f32_32x32x16_bf16 v[98:113], v[226:229], v[154:157], v[98:113]
	v_exp_f32_e32 v6, v243
	v_exp_f32_e32 v2, v245
	v_add_f32_e32 v7, v12, v246
	s_add_i32 s77, s74, 1
	s_cmp_ge_u32 s77, s51
	v_pk_add_f32 v[8:9], v[6:7], v[2:3]
	v_pk_fma_f32 v[242:243], v[132:133], v[4:5], v[4:5] op_sel:[0,1,0] op_sel_hi:[1,1,0]
	v_pk_add_f32 v[130:131], v[8:9], v[8:9] op_sel_hi:[0,1]
	s_waitcnt lgkmcnt(2)
	v_mfma_f32_32x32x16_bf16 v[82:97], v[230:233], v[154:157], v[82:97]
	v_pk_fma_f32 v[244:245], v[116:117], v[4:5], v[4:5] op_sel:[0,1,0] op_sel_hi:[1,1,0]
	v_exp_f32_e32 v7, v242
	v_exp_f32_e32 v247, v244
	v_exp_f32_e32 v8, v243
	v_exp_f32_e32 v130, v245
	v_add_f32_e32 v9, v7, v247
	v_cvt_pk_bf16_f32 v6, v12, v6
	v_cvt_pk_bf16_f32 v7, v7, v8
	s_waitcnt lgkmcnt(1)
	v_mfma_f32_32x32x16_bf16 v[98:113], v[234:237], v[158:161], v[98:113]
	v_pk_add_f32 v[10:11], v[8:9], v[130:131]
	v_pk_fma_f32 v[242:243], v[134:135], v[4:5], v[4:5] op_sel:[0,1,0] op_sel_hi:[1,1,0]
	v_pk_add_f32 v[132:133], v[10:11], v[10:11] op_sel_hi:[0,1]
	v_pk_fma_f32 v[244:245], v[118:119], v[4:5], v[4:5] op_sel:[0,1,0] op_sel_hi:[1,1,0]
	v_exp_f32_e32 v131, v244
	v_exp_f32_e32 v9, v242
	v_exp_f32_e32 v14, v243
	v_exp_f32_e32 v132, v245
	s_waitcnt lgkmcnt(0)
	v_mfma_f32_32x32x16_bf16 v[82:97], v[238:241], v[158:161], v[82:97]
	v_add_f32_e32 v15, v9, v131
	v_cvt_pk_bf16_f32 v8, v9, v14
	v_pk_add_f32 v[10:11], v[14:15], v[132:133]
	s_nop 0
	v_pk_add_f32 v[118:119], v[10:11], v[10:11] op_sel_hi:[0,1]
	v_pk_fma_f32 v[242:243], v[136:137], v[4:5], v[4:5] op_sel:[0,1,0] op_sel_hi:[1,1,0]
	v_exp_f32_e32 v15, v242
	v_pk_fma_f32 v[244:245], v[120:121], v[4:5], v[4:5] op_sel:[0,1,0] op_sel_hi:[1,1,0]
	v_exp_f32_e32 v133, v244
	v_exp_f32_e32 v16, v243
	v_exp_f32_e32 v118, v245
	v_add_f32_e32 v17, v15, v133
	v_cvt_pk_bf16_f32 v9, v15, v16
	v_pk_add_f32 v[10:11], v[16:17], v[118:119]
	s_nop 0
	v_pk_add_f32 v[120:121], v[10:11], v[10:11] op_sel_hi:[0,1]
	v_pk_fma_f32 v[242:243], v[138:139], v[4:5], v[4:5] op_sel:[0,1,0] op_sel_hi:[1,1,0]
	v_exp_f32_e32 v119, v242
	v_pk_fma_f32 v[244:245], v[122:123], v[4:5], v[4:5] op_sel:[0,1,0] op_sel_hi:[1,1,0]
	v_exp_f32_e32 v248, v244
	v_exp_f32_e32 v122, v243
	v_exp_f32_e32 v120, v245
	v_pk_fma_f32 v[242:243], v[140:141], v[4:5], v[4:5] op_sel:[0,1,0] op_sel_hi:[1,1,0]
	v_exp_f32_e32 v139, v242
	v_pk_fma_f32 v[244:245], v[124:125], v[4:5], v[4:5] op_sel:[0,1,0] op_sel_hi:[1,1,0]
	v_add_f32_e32 v123, v119, v248
	v_exp_f32_e32 v140, v244
	v_pk_add_f32 v[10:11], v[122:123], v[120:121]
	v_pk_fma_f32 v[250:251], v[144:145], v[4:5], v[4:5] op_sel:[0,1,0] op_sel_hi:[1,1,0]
	v_pk_add_f32 v[134:135], v[10:11], v[10:11] op_sel_hi:[0,1]
	v_exp_f32_e32 v136, v243
	v_exp_f32_e32 v134, v245
	ds_read_b64_tr_b16 v[10:11], v218 offset:8192
	ds_read_b64_tr_b16 v[12:13], v218 offset:9216
	ds_read_b64_tr_b16 v[14:15], v217 offset:8256
	ds_read_b64_tr_b16 v[16:17], v217 offset:9280
	ds_read_b64_tr_b16 v[114:115], v218 offset:10240
	ds_read_b64_tr_b16 v[116:117], v218 offset:11264
	s_waitcnt lgkmcnt(4)
	v_mfma_f32_32x32x16_bf16 v[66:81], v[10:13], v[6:9], v[66:81]
	v_pk_fma_f32 v[242:243], v[142:143], v[4:5], v[4:5] op_sel:[0,1,0] op_sel_hi:[1,1,0]
	v_exp_f32_e32 v121, v242
	v_exp_f32_e32 v124, v243
	v_exp_f32_e32 v141, v250
	v_add_f32_e32 v137, v139, v140
	ds_read_b64_tr_b16 v[10:11], v217 offset:10304
	ds_read_b64_tr_b16 v[12:13], v217 offset:11328
	s_waitcnt lgkmcnt(4)
	v_mfma_f32_32x32x16_bf16 v[50:65], v[14:17], v[6:9], v[50:65]
	v_exp_f32_e32 v138, v251
	v_cvt_pk_bf16_f32 v6, v119, v122
	v_cvt_pk_bf16_f32 v7, v139, v136
	v_cvt_pk_bf16_f32 v8, v121, v124
	v_cvt_pk_bf16_f32 v9, v141, v138
	v_pk_add_f32 v[14:15], v[136:137], v[134:135]
	s_waitcnt lgkmcnt(2)
	v_mfma_f32_32x32x16_bf16 v[66:81], v[114:117], v[6:9], v[66:81]
	v_add_f32_e64 v122, v14, v14
	v_add_f32_e64 v123, v14, v15
	v_pk_fma_f32 v[242:243], v[126:127], v[4:5], v[4:5] op_sel:[0,1,0] op_sel_hi:[1,1,0]
	v_exp_f32_e32 v126, v242
	ds_read_b64_tr_b16 v[14:15], v218 offset:12288
	ds_read_b64_tr_b16 v[16:17], v218 offset:13312
	v_exp_f32_e32 v122, v243
	v_add_f32_e32 v125, v121, v126
	s_waitcnt lgkmcnt(2)
	v_mfma_f32_32x32x16_bf16 v[50:65], v[10:13], v[6:9], v[50:65]
	v_cvt_pk_bf16_f32 v6, v246, v2
	v_cvt_pk_bf16_f32 v7, v247, v130
	v_cvt_pk_bf16_f32 v8, v131, v132
	v_cvt_pk_bf16_f32 v9, v133, v118
	ds_read_b64_tr_b16 v[10:11], v218 offset:14336
	ds_read_b64_tr_b16 v[12:13], v218 offset:15360
	v_pk_add_f32 v[114:115], v[124:125], v[122:123]
	v_pk_fma_f32 v[242:243], v[128:129], v[4:5], v[4:5] op_sel:[0,1,0] op_sel_hi:[1,1,0]
	s_waitcnt lgkmcnt(2)
	v_mfma_f32_32x32x16_bf16 v[66:81], v[14:17], v[6:9], v[66:81]
	ds_read_b64_tr_b16 v[14:15], v217 offset:12352
	ds_read_b64_tr_b16 v[16:17], v217 offset:13376
	v_add_f32_e64 v118, v114, v114
	v_add_f32_e64 v119, v114, v115
	ds_read_b64_tr_b16 v[114:115], v217 offset:14400
	ds_read_b64_tr_b16 v[116:117], v217 offset:15424
	v_exp_f32_e32 v2, v242
	v_exp_f32_e32 v118, v243
	v_cvt_pk_bf16_f32 v4, v248, v120
	s_waitcnt lgkmcnt(2)
	v_mfma_f32_32x32x16_bf16 v[50:65], v[14:17], v[6:9], v[50:65]
	v_cvt_pk_bf16_f32 v5, v140, v134
	v_cvt_pk_bf16_f32 v6, v126, v122
	v_cvt_pk_bf16_f32 v7, v2, v118
	v_add_f32_e32 v139, v141, v2
	v_add_f32_e64 v8, v138, v118
	v_add_f32_e64 v9, v139, v119
	v_add_f32_e32 v2, v8, v9
	v_mfma_f32_32x32x16_bf16 v[66:81], v[10:13], v[4:7], v[66:81]
	v_add_f32_e32 v214, v214, v2
	s_waitcnt lgkmcnt(0)
	v_mfma_f32_32x32x16_bf16 v[50:65], v[114:117], v[4:7], v[50:65]
	s_cbranch_scc1 .Lnq_780
	s_movk_i32 s76, 0x4000
	s_add_i32 s4, s74, 5
	s_cmp_ge_u32 s4, s51
	s_waitcnt vmcnt(1)
	ds_write_b128 v205, v[182:185] offset:32768
	s_waitcnt vmcnt(0)
	ds_write_b128 v212, v[178:181] offset:40960
	s_waitcnt lgkmcnt(0)
	s_barrier
	s_cbranch_scc1 .Lnq_762
	s_cmp_gt_u32 s4, s69
	s_cselect_b64 s[8:9], -1, 0
	s_mov_b32 s5, s52
	s_and_b64 s[8:9], s[8:9], exec
	s_cselect_b32 s4, s5, s4
	s_cselect_b32 s16, 0x1000, s65
	s_cselect_b32 s8, s64, 0x500
	s_lshl_b32 s4, s4, 6
	s_mov_b32 s9, s17
	v_mad_i64_i32 v[4:5], s[4:5], s4, v199, v[192:193]
	v_lshl_add_u64 v[6:7], v[4:5], 0, s[8:9]
	v_lshl_add_u64 v[4:5], v[4:5], 0, s[16:17]
	global_load_dwordx4 v[182:185], v[6:7], off
	global_load_dwordx4 v[178:181], v[4:5], off

; #define LAS __attribute__((address_space(3)))
; #define MFMA32(a, b, c) __builtin_amdgcn_mfma_f32_32x32x16_bf16((a), (b), (c), 0, 0, 0)
; DI float fexp2(float x) { return __builtin_amdgcn_exp2f(x); }
; DI s16x4 vtr(const LAS unsigned char* p) { return __builtin_bit_cast(s16x4, __builtin_amdgcn_ds_read_tr16_b64_v4i16((LAS v4i16_t*)p)); }
; DI void flash_qk(const LAS unsigned char* kb, const bf16x8 (&qf)[4], f32x16& p0, f32x16& p1, int r32, int h) {
;     ...
;     for (int s = 0; s < 4; ++s) {
;         const int off = r32 * 128 + (((2 * s + h) ^ sw) << 4);
;         const bf16x8 a0 = *(const LAS bf16x8*)(kb + off), a1 = *(const LAS bf16x8*)(kb + off + 4096);
;         p0 = MFMA32(a0, qf[s], p0); p1 = MFMA32(a1, qf[s], p1);
;     }
; DI void flash_pv(FState& st, f32x16& p0, f32x16& p1, bool rowon, const LAS unsigned char* vb, int lane) {
;     ...
;     const float cl = rowon ? SM_C : 0.0f;
;     const float bl = rowon ? ((st.m == NINF) ? 0.0f : -st.m * SM_C) : NINF;
;     float sum = 0.f;
; #pragma unroll
;     for (int r = 0; r < 16; ++r) { p0[r] = fexp2(__builtin_fmaf(p0[r], cl, bl)); p1[r] = fexp2(__builtin_fmaf(p1[r], cl, bl)); sum += p0[r] + p1[r]; }
;     st.l += sum;
;     const int h = lane >> 5;
;     const int vx = (((lane & 15) >> 3) & 1) * 64;
;     const LAS unsigned char* vp = vb + (4 * h + ((lane & 15) >> 2)) * 128 + ((lane >> 4) & 1) * 32 + (lane & 3) * 8;
; #pragma unroll
;     for (int sub = 0; sub < 2; ++sub)
; #pragma unroll
;         for (int s2 = 0; s2 < 2; ++s2) {
;             const bf16x8 pf = pack8h(sub ? p1 : p0, s2);
;             const LAS unsigned char* vq = vp + (32 * sub + 16 * s2) * 128;
;             { const s16x4 lo = vtr(vq + vx), hi = vtr(vq + 1024 + vx); const bf16x8 vf = {lo[0], lo[1], lo[2], lo[3], hi[0], hi[1], hi[2], hi[3]}; st.o0 = MFMA32(vf, pf, st.o0); }
;             { const s16x4 lo = vtr(vq + (64 - vx)), hi = vtr(vq + 1024 + (64 - vx)); const bf16x8 vf = {lo[0], lo[1], lo[2], lo[3], hi[0], hi[1], hi[2], hi[3]}; st.o1 = MFMA32(vf, pf, st.o1); }
;         }
.Lnq_778:
	s_or_b64 exec, exec, s[4:5]
	v_pk_fma_f32 v[242:243], v[98:99], v[4:5], v[4:5] op_sel:[0,1,0] op_sel_hi:[1,1,0]
	v_exp_f32_e32 v12, v242
	v_pk_fma_f32 v[244:245], v[82:83], v[4:5], v[4:5] op_sel:[0,1,0] op_sel_hi:[1,1,0]
	v_exp_f32_e32 v246, v244
	s_waitcnt lgkmcnt(3)
	v_mfma_f32_32x32x16_bf16 v[130:145], v[226:229], v[154:157], v[130:145]
	v_exp_f32_e32 v6, v243
	v_exp_f32_e32 v2, v245
	v_add_f32_e32 v7, v12, v246
	v_pk_add_f32 v[8:9], v[6:7], v[2:3]
	s_nop 0
	v_pk_add_f32 v[98:99], v[8:9], v[8:9] op_sel_hi:[0,1]
	v_pk_fma_f32 v[242:243], v[100:101], v[4:5], v[4:5] op_sel:[0,1,0] op_sel_hi:[1,1,0]
	v_pk_fma_f32 v[244:245], v[84:85], v[4:5], v[4:5] op_sel:[0,1,0] op_sel_hi:[1,1,0]
	s_waitcnt lgkmcnt(2)
	v_mfma_f32_32x32x16_bf16 v[114:129], v[230:233], v[154:157], v[114:129]
	v_exp_f32_e32 v7, v242
	v_exp_f32_e32 v247, v244
	v_exp_f32_e32 v8, v243
	v_exp_f32_e32 v98, v245
	v_add_f32_e32 v9, v7, v247
	v_cvt_pk_bf16_f32 v6, v12, v6
	v_cvt_pk_bf16_f32 v7, v7, v8
	v_pk_add_f32 v[10:11], v[8:9], v[98:99]
	s_waitcnt lgkmcnt(1)
	v_mfma_f32_32x32x16_bf16 v[130:145], v[234:237], v[158:161], v[130:145]
	v_pk_fma_f32 v[242:243], v[102:103], v[4:5], v[4:5] op_sel:[0,1,0] op_sel_hi:[1,1,0]
	v_pk_add_f32 v[100:101], v[10:11], v[10:11] op_sel_hi:[0,1]
	v_pk_fma_f32 v[244:245], v[86:87], v[4:5], v[4:5] op_sel:[0,1,0] op_sel_hi:[1,1,0]
	v_exp_f32_e32 v99, v244
	v_exp_f32_e32 v9, v242
	v_exp_f32_e32 v14, v243
	v_exp_f32_e32 v100, v245
	v_add_f32_e32 v15, v9, v99
	s_waitcnt lgkmcnt(0)
	v_mfma_f32_32x32x16_bf16 v[114:129], v[238:241], v[158:161], v[114:129]
	v_cvt_pk_bf16_f32 v8, v9, v14
	v_pk_add_f32 v[10:11], v[14:15], v[100:101]
	s_nop 0
	v_pk_add_f32 v[86:87], v[10:11], v[10:11] op_sel_hi:[0,1]
	v_pk_fma_f32 v[242:243], v[104:105], v[4:5], v[4:5] op_sel:[0,1,0] op_sel_hi:[1,1,0]
	v_exp_f32_e32 v15, v242
	v_pk_fma_f32 v[244:245], v[88:89], v[4:5], v[4:5] op_sel:[0,1,0] op_sel_hi:[1,1,0]
	v_exp_f32_e32 v101, v244
	v_exp_f32_e32 v16, v243
	v_exp_f32_e32 v86, v245
	v_add_f32_e32 v17, v15, v101
	v_cvt_pk_bf16_f32 v9, v15, v16
	v_pk_add_f32 v[10:11], v[16:17], v[86:87]
	s_nop 0
	v_pk_add_f32 v[88:89], v[10:11], v[10:11] op_sel_hi:[0,1]
	v_pk_fma_f32 v[242:243], v[106:107], v[4:5], v[4:5] op_sel:[0,1,0] op_sel_hi:[1,1,0]
	v_exp_f32_e32 v87, v242
	v_pk_fma_f32 v[244:245], v[90:91], v[4:5], v[4:5] op_sel:[0,1,0] op_sel_hi:[1,1,0]
	v_exp_f32_e32 v248, v244
	v_exp_f32_e32 v90, v243
	v_exp_f32_e32 v88, v245
	v_pk_fma_f32 v[242:243], v[108:109], v[4:5], v[4:5] op_sel:[0,1,0] op_sel_hi:[1,1,0]
	v_exp_f32_e32 v107, v242
	v_pk_fma_f32 v[244:245], v[92:93], v[4:5], v[4:5] op_sel:[0,1,0] op_sel_hi:[1,1,0]
	v_add_f32_e32 v91, v87, v248
	v_exp_f32_e32 v108, v244
	v_pk_add_f32 v[10:11], v[90:91], v[88:89]
	v_pk_fma_f32 v[250:251], v[112:113], v[4:5], v[4:5] op_sel:[0,1,0] op_sel_hi:[1,1,0]
	v_pk_add_f32 v[102:103], v[10:11], v[10:11] op_sel_hi:[0,1]
	v_exp_f32_e32 v104, v243
	v_exp_f32_e32 v102, v245
	ds_read_b64_tr_b16 v[10:11], v218 offset:24576
	ds_read_b64_tr_b16 v[12:13], v218 offset:25600
	ds_read_b64_tr_b16 v[14:15], v217 offset:24640
	ds_read_b64_tr_b16 v[16:17], v217 offset:25664
	ds_read_b64_tr_b16 v[82:83], v218 offset:26624
	ds_read_b64_tr_b16 v[84:85], v218 offset:27648
	s_waitcnt lgkmcnt(4)
	v_mfma_f32_32x32x16_bf16 v[66:81], v[10:13], v[6:9], v[66:81]
	v_pk_fma_f32 v[242:243], v[110:111], v[4:5], v[4:5] op_sel:[0,1,0] op_sel_hi:[1,1,0]
	v_exp_f32_e32 v93, v242
	v_exp_f32_e32 v92, v243
	v_exp_f32_e32 v110, v250
	v_add_f32_e32 v105, v107, v108
	ds_read_b64_tr_b16 v[10:11], v217 offset:26688
	ds_read_b64_tr_b16 v[12:13], v217 offset:27712
	s_waitcnt lgkmcnt(4)
	v_mfma_f32_32x32x16_bf16 v[50:65], v[14:17], v[6:9], v[50:65]
	v_exp_f32_e32 v106, v251
	v_cvt_pk_bf16_f32 v6, v87, v90
	v_cvt_pk_bf16_f32 v7, v107, v104
	v_cvt_pk_bf16_f32 v8, v93, v92
	v_cvt_pk_bf16_f32 v9, v110, v106
	v_pk_add_f32 v[14:15], v[104:105], v[102:103]
	s_waitcnt lgkmcnt(2)
	v_mfma_f32_32x32x16_bf16 v[66:81], v[82:85], v[6:9], v[66:81]
	v_add_f32_e64 v90, v14, v14
	v_add_f32_e64 v91, v14, v15
	v_pk_fma_f32 v[242:243], v[94:95], v[4:5], v[4:5] op_sel:[0,1,0] op_sel_hi:[1,1,0]
	v_exp_f32_e32 v94, v242
	ds_read_b64_tr_b16 v[14:15], v218 offset:28672
	ds_read_b64_tr_b16 v[16:17], v218 offset:29696
	v_exp_f32_e32 v90, v243
	v_add_f32_e32 v93, v93, v94
	s_waitcnt lgkmcnt(2)
	v_mfma_f32_32x32x16_bf16 v[50:65], v[10:13], v[6:9], v[50:65]
	v_cvt_pk_bf16_f32 v6, v246, v2
	v_cvt_pk_bf16_f32 v7, v247, v98
	v_cvt_pk_bf16_f32 v8, v99, v100
	v_cvt_pk_bf16_f32 v9, v101, v86
	ds_read_b64_tr_b16 v[10:11], v218 offset:30720
	ds_read_b64_tr_b16 v[12:13], v218 offset:31744
	v_pk_add_f32 v[82:83], v[92:93], v[90:91]
	v_pk_fma_f32 v[242:243], v[96:97], v[4:5], v[4:5] op_sel:[0,1,0] op_sel_hi:[1,1,0]
	s_waitcnt lgkmcnt(2)
	v_mfma_f32_32x32x16_bf16 v[66:81], v[14:17], v[6:9], v[66:81]
	ds_read_b64_tr_b16 v[14:15], v217 offset:28736
	ds_read_b64_tr_b16 v[16:17], v217 offset:29760
	v_add_f32_e64 v86, v82, v82
	v_add_f32_e64 v87, v82, v83
	ds_read_b64_tr_b16 v[82:83], v217 offset:30784
	ds_read_b64_tr_b16 v[84:85], v217 offset:31808
	v_exp_f32_e32 v2, v242
	v_exp_f32_e32 v86, v243
	v_cvt_pk_bf16_f32 v4, v248, v88
	s_waitcnt lgkmcnt(2)
	v_mfma_f32_32x32x16_bf16 v[50:65], v[14:17], v[6:9], v[50:65]
	v_cvt_pk_bf16_f32 v5, v108, v102
	v_cvt_pk_bf16_f32 v6, v94, v90
	v_cvt_pk_bf16_f32 v7, v2, v86
	v_add_f32_e32 v107, v110, v2
	v_add_f32_e64 v8, v106, v86
	v_add_f32_e64 v9, v107, v87
	v_add_f32_e32 v2, v8, v9
	v_mfma_f32_32x32x16_bf16 v[66:81], v[10:13], v[4:7], v[66:81]
	v_add_f32_e32 v214, v214, v2
	s_waitcnt lgkmcnt(0)
	v_mfma_f32_32x32x16_bf16 v[50:65], v[82:85], v[4:7], v[50:65]
	s_add_i32 s76, s74, 2
	s_cmp_ge_u32 s76, s51
	s_cbranch_scc0 .Lnq_781

; #define LAS __attribute__((address_space(3)))
; #define MFMA32(a, b, c) __builtin_amdgcn_mfma_f32_32x32x16_bf16((a), (b), (c), 0, 0, 0)
; DI float fexp2(float x) { return __builtin_amdgcn_exp2f(x); }
; DI s16x4 vtr(const LAS unsigned char* p) { return __builtin_bit_cast(s16x4, __builtin_amdgcn_ds_read_tr16_b64_v4i16((LAS v4i16_t*)p)); }
; DI void flash_qk(const LAS unsigned char* kb, const bf16x8 (&qf)[4], f32x16& p0, f32x16& p1, int r32, int h) {
;     ...
;     for (int s = 0; s < 4; ++s) {
;         const int off = r32 * 128 + (((2 * s + h) ^ sw) << 4);
;         const bf16x8 a0 = *(const LAS bf16x8*)(kb + off), a1 = *(const LAS bf16x8*)(kb + off + 4096);
;         p0 = MFMA32(a0, qf[s], p0); p1 = MFMA32(a1, qf[s], p1);
;     }
; DI void flash_pv(FState& st, f32x16& p0, f32x16& p1, bool rowon, const LAS unsigned char* vb, int lane) {
;     ...
;     const float cl = rowon ? SM_C : 0.0f;
;     const float bl = rowon ? ((st.m == NINF) ? 0.0f : -st.m * SM_C) : NINF;
;     float sum = 0.f;
; #pragma unroll
;     for (int r = 0; r < 16; ++r) { p0[r] = fexp2(__builtin_fmaf(p0[r], cl, bl)); p1[r] = fexp2(__builtin_fmaf(p1[r], cl, bl)); sum += p0[r] + p1[r]; }
;     st.l += sum;
;     const int h = lane >> 5;
;     const int vx = (((lane & 15) >> 3) & 1) * 64;
;     const LAS unsigned char* vp = vb + (4 * h + ((lane & 15) >> 2)) * 128 + ((lane >> 4) & 1) * 32 + (lane & 3) * 8;
; #pragma unroll
;     for (int sub = 0; sub < 2; ++sub)
; #pragma unroll
;         for (int s2 = 0; s2 < 2; ++s2) {
;             const bf16x8 pf = pack8h(sub ? p1 : p0, s2);
;             const LAS unsigned char* vq = vp + (32 * sub + 16 * s2) * 128;
;             { const s16x4 lo = vtr(vq + vx), hi = vtr(vq + 1024 + vx); const bf16x8 vf = {lo[0], lo[1], lo[2], lo[3], hi[0], hi[1], hi[2], hi[3]}; st.o0 = MFMA32(vf, pf, st.o0); }
;             { const s16x4 lo = vtr(vq + (64 - vx)), hi = vtr(vq + 1024 + (64 - vx)); const bf16x8 vf = {lo[0], lo[1], lo[2], lo[3], hi[0], hi[1], hi[2], hi[3]}; st.o1 = MFMA32(vf, pf, st.o1); }
;         }
.Lnq_799:
	s_or_b64 exec, exec, s[4:5]
	v_pk_fma_f32 v[242:243], v[130:131], v[4:5], v[4:5] op_sel:[0,1,0] op_sel_hi:[1,1,0]
	v_exp_f32_e32 v246, v242
	v_pk_fma_f32 v[244:245], v[114:115], v[4:5], v[4:5] op_sel:[0,1,0] op_sel_hi:[1,1,0]
	v_exp_f32_e32 v247, v244
	s_waitcnt lgkmcnt(3)
	v_mfma_f32_32x32x16_bf16 v[98:113], v[226:229], v[154:157], v[98:113]
	v_exp_f32_e32 v10, v243
	v_exp_f32_e32 v2, v245
	v_add_f32_e32 v11, v246, v247
	v_pk_add_f32 v[6:7], v[10:11], v[2:3]
	s_nop 0
	v_pk_add_f32 v[130:131], v[6:7], v[6:7] op_sel_hi:[0,1]
	v_pk_fma_f32 v[242:243], v[132:133], v[4:5], v[4:5] op_sel:[0,1,0] op_sel_hi:[1,1,0]
	v_exp_f32_e32 v11, v242
	s_waitcnt lgkmcnt(2)
	v_mfma_f32_32x32x16_bf16 v[82:97], v[230:233], v[154:157], v[82:97]
	v_pk_fma_f32 v[244:245], v[116:117], v[4:5], v[4:5] op_sel:[0,1,0] op_sel_hi:[1,1,0]
	v_exp_f32_e32 v248, v244
	v_exp_f32_e32 v12, v243
	v_exp_f32_e32 v130, v245
	v_add_f32_e32 v13, v11, v248
	v_cvt_pk_bf16_f32 v10, v246, v10
	v_cvt_pk_bf16_f32 v11, v11, v12
	v_pk_add_f32 v[6:7], v[12:13], v[130:131]
	s_waitcnt lgkmcnt(1)
	v_mfma_f32_32x32x16_bf16 v[98:113], v[234:237], v[158:161], v[98:113]
	s_nop 0
	v_pk_add_f32 v[132:133], v[6:7], v[6:7] op_sel_hi:[0,1]
	v_pk_fma_f32 v[242:243], v[134:135], v[4:5], v[4:5] op_sel:[0,1,0] op_sel_hi:[1,1,0]
	v_exp_f32_e32 v13, v242
	v_pk_fma_f32 v[244:245], v[118:119], v[4:5], v[4:5] op_sel:[0,1,0] op_sel_hi:[1,1,0]
	v_exp_f32_e32 v131, v244
	v_exp_f32_e32 v14, v243
	v_exp_f32_e32 v132, v245
	s_waitcnt lgkmcnt(0)
	v_mfma_f32_32x32x16_bf16 v[82:97], v[238:241], v[158:161], v[82:97]
	v_add_f32_e32 v15, v13, v131
	v_cvt_pk_bf16_f32 v12, v13, v14
	v_pk_add_f32 v[6:7], v[14:15], v[132:133]
	s_nop 0
	v_pk_add_f32 v[118:119], v[6:7], v[6:7] op_sel_hi:[0,1]
	v_pk_fma_f32 v[242:243], v[136:137], v[4:5], v[4:5] op_sel:[0,1,0] op_sel_hi:[1,1,0]
	v_exp_f32_e32 v15, v242
	v_pk_fma_f32 v[244:245], v[120:121], v[4:5], v[4:5] op_sel:[0,1,0] op_sel_hi:[1,1,0]
	v_exp_f32_e32 v133, v244
	v_exp_f32_e32 v16, v243
	v_exp_f32_e32 v118, v245
	v_add_f32_e32 v17, v15, v133
	v_cvt_pk_bf16_f32 v13, v15, v16
	v_pk_add_f32 v[6:7], v[16:17], v[118:119]
	s_nop 0
	v_pk_add_f32 v[120:121], v[6:7], v[6:7] op_sel_hi:[0,1]
	v_pk_fma_f32 v[242:243], v[138:139], v[4:5], v[4:5] op_sel:[0,1,0] op_sel_hi:[1,1,0]
	v_exp_f32_e32 v119, v242
	v_pk_fma_f32 v[244:245], v[122:123], v[4:5], v[4:5] op_sel:[0,1,0] op_sel_hi:[1,1,0]
	v_exp_f32_e32 v249, v244
	v_exp_f32_e32 v122, v243
	v_exp_f32_e32 v120, v245
	v_pk_fma_f32 v[242:243], v[140:141], v[4:5], v[4:5] op_sel:[0,1,0] op_sel_hi:[1,1,0]
	v_exp_f32_e32 v139, v242
	v_pk_fma_f32 v[244:245], v[124:125], v[4:5], v[4:5] op_sel:[0,1,0] op_sel_hi:[1,1,0]
	v_add_f32_e32 v123, v119, v249
	v_exp_f32_e32 v140, v244
	v_pk_add_f32 v[6:7], v[122:123], v[120:121]
	v_pk_fma_f32 v[250:251], v[144:145], v[4:5], v[4:5] op_sel:[0,1,0] op_sel_hi:[1,1,0]
	v_pk_add_f32 v[134:135], v[6:7], v[6:7] op_sel_hi:[0,1]
	v_exp_f32_e32 v136, v243
	v_exp_f32_e32 v134, v245
	ds_read_b64_tr_b16 v[6:7], v218 offset:40960
	ds_read_b64_tr_b16 v[8:9], v218 offset:41984
	ds_read_b64_tr_b16 v[14:15], v217 offset:41024
	ds_read_b64_tr_b16 v[16:17], v217 offset:42048
	ds_read_b64_tr_b16 v[114:115], v218 offset:43008
	ds_read_b64_tr_b16 v[116:117], v218 offset:44032
	s_waitcnt lgkmcnt(4)
	v_mfma_f32_32x32x16_bf16 v[66:81], v[6:9], v[10:13], v[66:81]
	v_pk_fma_f32 v[242:243], v[142:143], v[4:5], v[4:5] op_sel:[0,1,0] op_sel_hi:[1,1,0]
	v_exp_f32_e32 v121, v242
	v_exp_f32_e32 v124, v243
	v_exp_f32_e32 v141, v250
	v_add_f32_e32 v137, v139, v140
	ds_read_b64_tr_b16 v[6:7], v217 offset:43072
	ds_read_b64_tr_b16 v[8:9], v217 offset:44096
	s_waitcnt lgkmcnt(4)
	v_mfma_f32_32x32x16_bf16 v[50:65], v[14:17], v[10:13], v[50:65]
	v_exp_f32_e32 v138, v251
	v_cvt_pk_bf16_f32 v10, v119, v122
	v_cvt_pk_bf16_f32 v11, v139, v136
	v_cvt_pk_bf16_f32 v12, v121, v124
	v_cvt_pk_bf16_f32 v13, v141, v138
	v_pk_add_f32 v[14:15], v[136:137], v[134:135]
	s_waitcnt lgkmcnt(2)
	v_mfma_f32_32x32x16_bf16 v[66:81], v[114:117], v[10:13], v[66:81]
	v_add_f32_e64 v122, v14, v14
	v_add_f32_e64 v123, v14, v15
	v_pk_fma_f32 v[242:243], v[126:127], v[4:5], v[4:5] op_sel:[0,1,0] op_sel_hi:[1,1,0]
	v_exp_f32_e32 v126, v242
	ds_read_b64_tr_b16 v[14:15], v218 offset:45056
	ds_read_b64_tr_b16 v[16:17], v218 offset:46080
	v_exp_f32_e32 v122, v243
	v_add_f32_e32 v125, v121, v126
	s_waitcnt lgkmcnt(2)
	v_mfma_f32_32x32x16_bf16 v[50:65], v[6:9], v[10:13], v[50:65]
	v_cvt_pk_bf16_f32 v6, v247, v2
	v_cvt_pk_bf16_f32 v7, v248, v130
	v_cvt_pk_bf16_f32 v8, v131, v132
	v_cvt_pk_bf16_f32 v9, v133, v118
	ds_read_b64_tr_b16 v[10:11], v218 offset:47104
	ds_read_b64_tr_b16 v[12:13], v218 offset:48128
	v_pk_add_f32 v[114:115], v[124:125], v[122:123]
	v_pk_fma_f32 v[242:243], v[128:129], v[4:5], v[4:5] op_sel:[0,1,0] op_sel_hi:[1,1,0]
	s_waitcnt lgkmcnt(2)
	v_mfma_f32_32x32x16_bf16 v[66:81], v[14:17], v[6:9], v[66:81]
	ds_read_b64_tr_b16 v[14:15], v217 offset:45120
	ds_read_b64_tr_b16 v[16:17], v217 offset:46144
	v_add_f32_e64 v118, v114, v114
	v_add_f32_e64 v119, v114, v115
	ds_read_b64_tr_b16 v[114:115], v217 offset:47168
	ds_read_b64_tr_b16 v[116:117], v217 offset:48192
	v_exp_f32_e32 v2, v242
	v_exp_f32_e32 v118, v243
	v_cvt_pk_bf16_f32 v4, v249, v120
	s_waitcnt lgkmcnt(2)
	v_mfma_f32_32x32x16_bf16 v[50:65], v[14:17], v[6:9], v[50:65]
	v_cvt_pk_bf16_f32 v5, v140, v134
	v_cvt_pk_bf16_f32 v6, v126, v122
	v_cvt_pk_bf16_f32 v7, v2, v118
	v_add_f32_e32 v139, v141, v2
	v_add_f32_e64 v8, v138, v118
	v_add_f32_e64 v9, v139, v119
	v_add_f32_e32 v2, v8, v9
	v_mfma_f32_32x32x16_bf16 v[66:81], v[10:13], v[4:7], v[66:81]
	v_add_f32_e32 v214, v214, v2
	s_waitcnt lgkmcnt(0)
	v_mfma_f32_32x32x16_bf16 v[50:65], v[114:117], v[4:7], v[50:65]
	s_add_i32 s52, s52, -3
	s_andn2_b64 vcc, exec, s[6:7]
	s_add_i32 s53, s53, 0xc000
	s_cbranch_vccz .LBB0_712
